# prologue x->bf16 residual copy: the four 1 KB row loads issued together with counted vmcnt(3) waits instead of four load-wait-store round trips per row
# baseline (speedup 1.0000x reference)
.LBB0_371:
	global_load_dwordx4 v[10:13], v[6:7], off offset:-3072
	global_load_dwordx4 v[14:17], v[6:7], off offset:-2048
	global_load_dwordx4 v[18:21], v[6:7], off offset:-1024
	global_load_dwordx4 v[22:25], v[6:7], off
	s_waitcnt vmcnt(3)
	s_nop 0
	v_cvt_pk_bf16_f32 v26, v10, v11
	s_nop 1
	s_nop 0
	v_cvt_pk_bf16_f32 v27, v12, v13
	s_nop 1
	global_store_dwordx2 v[4:5], v[26:27], off offset:-1024
	s_waitcnt vmcnt(3)
	s_nop 0
	v_cvt_pk_bf16_f32 v28, v14, v15
	s_nop 1
	s_nop 0
	v_cvt_pk_bf16_f32 v29, v16, v17
	s_nop 1
	global_store_dwordx2 v[4:5], v[28:29], off offset:-512
	s_waitcnt vmcnt(3)
	s_nop 0
	v_cvt_pk_bf16_f32 v30, v18, v19
	s_nop 1
	s_nop 0
	v_cvt_pk_bf16_f32 v31, v20, v21
	s_nop 1
	global_store_dwordx2 v[4:5], v[30:31], off
	v_and_b32_e32 v1, 64, v214
	s_waitcnt lgkmcnt(0)
	v_xor_b32_e32 v9, 32, v214
	v_add_u32_e32 v1, 64, v1
	v_cmp_lt_i32_e32 vcc, v9, v1
	v_mul_f32_e32 v11, v11, v11
	v_fmac_f32_e32 v11, v10, v10
	v_fmac_f32_e32 v11, v12, v12
	v_fmac_f32_e32 v11, v13, v13
	v_mul_f32_e32 v10, v15, v15
	v_fmac_f32_e32 v10, v14, v14
	v_fmac_f32_e32 v10, v16, v16
	v_fmac_f32_e32 v10, v17, v17
	v_add_f32_e32 v10, v11, v10
	v_mul_f32_e32 v11, v19, v19
	v_fmac_f32_e32 v11, v18, v18
	v_fmac_f32_e32 v11, v20, v20
	v_fmac_f32_e32 v11, v21, v21
	v_add_f32_e32 v10, v10, v11
	s_waitcnt vmcnt(3)
	v_mul_f32_e32 v11, v23, v23
	v_fmac_f32_e32 v11, v22, v22
	v_fmac_f32_e32 v11, v24, v24
	v_cndmask_b32_e32 v9, v214, v9, vcc
	v_fmac_f32_e32 v11, v25, v25
	v_lshlrev_b32_e32 v9, 2, v9
	v_add_f32_e32 v10, v10, v11
	ds_bpermute_b32 v9, v9, v10
	v_xor_b32_e32 v11, 16, v214
	v_cmp_lt_i32_e32 vcc, v11, v1
	s_waitcnt lgkmcnt(0)
	v_add_f32_e32 v9, v10, v9
	v_cndmask_b32_e32 v11, v214, v11, vcc
	v_lshlrev_b32_e32 v11, 2, v11
	ds_bpermute_b32 v10, v11, v9
	v_xor_b32_e32 v11, 8, v214
	v_cmp_lt_i32_e32 vcc, v11, v1
	s_waitcnt lgkmcnt(0)
	v_add_f32_e32 v9, v9, v10
	v_cndmask_b32_e32 v11, v214, v11, vcc
	v_lshlrev_b32_e32 v11, 2, v11
	ds_bpermute_b32 v10, v11, v9
	v_xor_b32_e32 v11, 4, v214
	v_cmp_lt_i32_e32 vcc, v11, v1
	s_waitcnt lgkmcnt(0)
	v_add_f32_e32 v9, v9, v10
	v_cndmask_b32_e32 v11, v214, v11, vcc
	v_lshlrev_b32_e32 v11, 2, v11
	ds_bpermute_b32 v10, v11, v9
	v_xor_b32_e32 v11, 2, v214
	v_cmp_lt_i32_e32 vcc, v11, v1
	s_waitcnt lgkmcnt(0)
	v_add_f32_e32 v9, v9, v10
	v_cndmask_b32_e32 v11, v214, v11, vcc
	v_lshlrev_b32_e32 v11, 2, v11
	ds_bpermute_b32 v10, v11, v9
	v_xor_b32_e32 v11, 1, v214
	v_cmp_lt_i32_e32 vcc, v11, v1
	s_waitcnt lgkmcnt(0)
	v_add_f32_e32 v1, v9, v10
	v_cndmask_b32_e32 v11, v214, v11, vcc
	v_lshlrev_b32_e32 v9, 2, v11
	ds_bpermute_b32 v9, v9, v1
	s_nop 0
	v_cvt_pk_bf16_f32 v10, v22, v23
	s_nop 1
	s_nop 0
	v_cvt_pk_bf16_f32 v11, v24, v25
	s_nop 1
	global_store_dwordx2 v[4:5], v[10:11], off offset:512
	s_mov_b64 s[40:41], exec
	v_readlane_b32 s10, v254, 21
	v_readlane_b32 s11, v254, 22
	s_and_b64 s[10:11], s[40:41], s[10:11]
	s_mov_b64 exec, s[10:11]
	s_cbranch_execz .LBB0_370
	s_waitcnt lgkmcnt(0)
	v_add_f32_e32 v1, v1, v9
	v_fma_f32 v1, v1, s91, 0.5
	v_trunc_f32_e32 v1, v1
	v_mul_f32_e32 v9, 0x2f800000, v1
	v_floor_f32_e32 v9, v9
	v_fmac_f32_e32 v1, 0xcf800000, v9
	v_cvt_u32_f32_e32 v10, v1
	v_cvt_u32_f32_e32 v11, v9
	global_store_dwordx2 v[2:3], v[10:11], off
	s_branch .LBB0_370
